# attention epilogue: map-1 partial-O LDS reads issued four at a time into separate quads (no per-read wait ladder)
# speedup vs baseline: 1.0013x; 1.0013x over previous
; __device__ __forceinline__ void phase_attn(KP P, char* smem, const int wv) {
;     ...
;     if (cm == 0 && wave_valid) {
; #pragma unroll
;       for (int qt = 0; qt < 2; ++qt) {
;         float rl = 1.f / lrun[qt];
;         float ss = 0.f;
; #pragma unroll
;         for (int et = 0; et < 8; ++et) {
;           f32x4 o1 = *(const f32x4*)(sO + (rg * 32 + qt * 16 + fr) * A_LDO + et * 16 + fq * 4);
;           f32x4 o = oacc[qt][et] * rl - o1 * lam;
;           oacc[qt][et] = o;
;           ss += o[0] * o[0] + o[1] * o[1] + o[2] * o[2] + o[3] * o[3];
;         }
;         ss = xsum_16_32(ss);
;         float rstd = rsqrtf(ss * (1.f / 128.f) + EPS) * (1.f - LAMBDA_INIT);
;         bfu* dst = ao + (size_t)(qrow0 + rg * 32 + qt * 16 + fr) * 1024 + h * 128;
;         int fqe = fq;
;         asm volatile("" : "+v"(fqe));
; #pragma unroll
;         for (int et = 0; et < 8; ++et) {
;           int e0 = et * 16 + fqe * 4;
;           f32x4 sw = *(const f32x4*)(subln + e0);
;           uint2 pk;
;           pk.x = cvt_pk_bf16(oacc[qt][et][0] * rstd * sw[0], oacc[qt][et][1] * rstd * sw[1]);
;           pk.y = cvt_pk_bf16(oacc[qt][et][2] * rstd * sw[2], oacc[qt][et][3] * rstd * sw[3]);
;           *(uint2*)(dst + e0) = pk;
;         }
.LBB0_81:
	v_readlane_b32 s8, v241, 14
	v_readlane_b32 s9, v241, 15
	s_and_b64 s[6:7], s[8:9], s[6:7]
	s_andn2_b64 vcc, exec, s[6:7]
	s_waitcnt lgkmcnt(0)
	s_barrier
	s_cbranch_vccnz .LBB0_30
	v_div_scale_f32 v84, s[8:9], v83, v83, 1.0
	v_rcp_f32_e32 v85, v84
	v_add_u32_e32 v82, s62, v179
	s_lshl_b64 s[6:7], s[20:21], 1
	s_add_u32 s6, s31, s6
	v_fma_f32 v86, -v84, v85, 1.0
	v_fmac_f32_e32 v85, v86, v85
	v_div_scale_f32 v86, vcc, 1.0, v83, 1.0
	v_mul_f32_e32 v87, v86, v85
	v_fma_f32 v88, -v84, v87, v86
	v_fmac_f32_e32 v87, v88, v85
	ds_read_b128 v[220:223], v182
	ds_read_b128 v[224:227], v182 offset:64
	ds_read_b128 v[228:231], v182 offset:128
	ds_read_b128 v[232:235], v182 offset:192
	v_fma_f32 v84, -v84, v87, v86
	v_div_fmas_f32 v84, v84, v85, v87
	v_div_fixup_f32 v86, v84, v83, 1.0
	s_addc_u32 s7, s34, s7
	s_waitcnt lgkmcnt(0)
	v_pk_mul_f32 v[88:89], v[122:123], v[220:221]
	v_pk_mul_f32 v[84:85], v[124:125], v[222:223]
	v_pk_fma_f32 v[78:79], v[78:79], v[86:87], v[88:89] op_sel_hi:[1,0,1] neg_lo:[0,0,1] neg_hi:[0,0,1]
	v_pk_fma_f32 v[80:81], v[80:81], v[86:87], v[84:85] op_sel_hi:[1,0,1] neg_lo:[0,0,1] neg_hi:[0,0,1]
	v_mul_f32_e32 v83, v79, v79
	v_fmac_f32_e32 v83, v78, v78
	v_fmac_f32_e32 v83, v80, v80
	s_waitcnt lgkmcnt(0)
	v_pk_mul_f32 v[88:89], v[122:123], v[224:225]
	v_pk_mul_f32 v[84:85], v[124:125], v[226:227]
	v_pk_fma_f32 v[74:75], v[74:75], v[86:87], v[88:89] op_sel_hi:[1,0,1] neg_lo:[0,0,1] neg_hi:[0,0,1]
	v_pk_fma_f32 v[76:77], v[76:77], v[86:87], v[84:85] op_sel_hi:[1,0,1] neg_lo:[0,0,1] neg_hi:[0,0,1]
	v_mul_f32_e32 v84, v75, v75
	v_fmac_f32_e32 v84, v74, v74
	v_fmac_f32_e32 v84, v76, v76
	v_fmac_f32_e32 v83, v81, v81
	v_fmac_f32_e32 v84, v77, v77
	s_waitcnt lgkmcnt(0)
	v_pk_mul_f32 v[88:89], v[122:123], v[228:229]
	v_add_f32_e32 v83, v83, v84
	v_pk_mul_f32 v[84:85], v[124:125], v[230:231]
	v_pk_fma_f32 v[70:71], v[70:71], v[86:87], v[88:89] op_sel_hi:[1,0,1] neg_lo:[0,0,1] neg_hi:[0,0,1]
	v_pk_fma_f32 v[72:73], v[72:73], v[86:87], v[84:85] op_sel_hi:[1,0,1] neg_lo:[0,0,1] neg_hi:[0,0,1]
	v_mul_f32_e32 v84, v71, v71
	v_fmac_f32_e32 v84, v70, v70
	v_fmac_f32_e32 v84, v72, v72
	v_fmac_f32_e32 v84, v73, v73
	s_waitcnt lgkmcnt(0)
	v_pk_mul_f32 v[88:89], v[122:123], v[232:233]
	v_add_f32_e32 v83, v83, v84
	v_pk_mul_f32 v[84:85], v[124:125], v[234:235]
	v_pk_fma_f32 v[66:67], v[66:67], v[86:87], v[88:89] op_sel_hi:[1,0,1] neg_lo:[0,0,1] neg_hi:[0,0,1]
	ds_read_b128 v[220:223], v182 offset:256
	ds_read_b128 v[224:227], v182 offset:320
	ds_read_b128 v[228:231], v182 offset:384
	ds_read_b128 v[232:235], v182 offset:448
	v_pk_fma_f32 v[68:69], v[68:69], v[86:87], v[84:85] op_sel_hi:[1,0,1] neg_lo:[0,0,1] neg_hi:[0,0,1]
	v_mul_f32_e32 v84, v67, v67
	v_fmac_f32_e32 v84, v66, v66
	v_fmac_f32_e32 v84, v68, v68
	v_fmac_f32_e32 v84, v69, v69
	s_waitcnt lgkmcnt(0)
	v_pk_mul_f32 v[88:89], v[122:123], v[220:221]
	v_add_f32_e32 v83, v83, v84
	v_pk_mul_f32 v[84:85], v[124:125], v[222:223]
	v_pk_fma_f32 v[62:63], v[62:63], v[86:87], v[88:89] op_sel_hi:[1,0,1] neg_lo:[0,0,1] neg_hi:[0,0,1]
	v_pk_fma_f32 v[64:65], v[64:65], v[86:87], v[84:85] op_sel_hi:[1,0,1] neg_lo:[0,0,1] neg_hi:[0,0,1]
	v_mul_f32_e32 v84, v63, v63
	v_fmac_f32_e32 v84, v62, v62
	v_fmac_f32_e32 v84, v64, v64
	v_fmac_f32_e32 v84, v65, v65
	s_waitcnt lgkmcnt(0)
	v_pk_mul_f32 v[88:89], v[122:123], v[224:225]
	v_add_f32_e32 v83, v83, v84
	v_pk_mul_f32 v[84:85], v[124:125], v[226:227]
	v_pk_fma_f32 v[58:59], v[58:59], v[86:87], v[88:89] op_sel_hi:[1,0,1] neg_lo:[0,0,1] neg_hi:[0,0,1]
	v_pk_fma_f32 v[60:61], v[60:61], v[86:87], v[84:85] op_sel_hi:[1,0,1] neg_lo:[0,0,1] neg_hi:[0,0,1]
	v_mul_f32_e32 v84, v59, v59
	v_fmac_f32_e32 v84, v58, v58
	v_fmac_f32_e32 v84, v60, v60
	v_fmac_f32_e32 v84, v61, v61
	s_waitcnt lgkmcnt(0)
	v_pk_mul_f32 v[88:89], v[122:123], v[228:229]
	v_add_f32_e32 v83, v83, v84
	v_pk_mul_f32 v[84:85], v[124:125], v[230:231]
	v_pk_fma_f32 v[54:55], v[54:55], v[86:87], v[88:89] op_sel_hi:[1,0,1] neg_lo:[0,0,1] neg_hi:[0,0,1]
	v_pk_fma_f32 v[56:57], v[56:57], v[86:87], v[84:85] op_sel_hi:[1,0,1] neg_lo:[0,0,1] neg_hi:[0,0,1]
	v_mul_f32_e32 v84, v55, v55
	v_fmac_f32_e32 v84, v54, v54
	v_fmac_f32_e32 v84, v56, v56
	v_fmac_f32_e32 v84, v57, v57
	v_add_f32_e32 v83, v83, v84
	s_waitcnt lgkmcnt(0)
	v_pk_mul_f32 v[84:85], v[124:125], v[234:235]
	v_pk_mul_f32 v[88:89], v[122:123], v[232:233]
	v_pk_fma_f32 v[84:85], v[52:53], v[86:87], v[84:85] op_sel_hi:[1,0,1] neg_lo:[0,0,1] neg_hi:[0,0,1]
	v_pk_fma_f32 v[86:87], v[50:51], v[86:87], v[88:89] op_sel_hi:[1,0,1] neg_lo:[0,0,1] neg_hi:[0,0,1]
	s_nop 0
	v_mul_f32_e32 v50, v87, v87
	v_fmac_f32_e32 v50, v86, v86
	v_fmac_f32_e32 v50, v84, v84
	v_fmac_f32_e32 v50, v85, v85
	v_add_f32_e32 v50, v83, v50
	v_mov_b32_e32 v51, v50
	s_nop 1
	v_permlane16_swap_b32_e32 v50, v51
	v_add_f32_e32 v50, v50, v51
	v_mov_b32_e32 v51, v50
	s_nop 1
	v_permlane32_swap_b32_e32 v50, v51
	v_add_f32_e32 v50, v50, v51
	v_fmamk_f32 v50, v50, 0x3c000000, v146
	v_cmp_gt_f32_e32 vcc, s33, v50
	v_mul_f32_e32 v51, 0x4b800000, v50
	v_ashrrev_i32_e32 v83, 31, v82
	v_cndmask_b32_e32 v50, v50, v51, vcc
	v_rsq_f32_e32 v50, v50
	s_nop 0
	v_mul_f32_e32 v51, 0x45800000, v50
	v_cndmask_b32_e32 v50, v50, v51, vcc
	v_mul_f32_e32 v95, 0x3f24fd5c, v50
	v_lshlrev_b64 v[50:51], 11, v[82:83]
	v_lshl_add_u64 v[90:91], s[6:7], 0, v[50:51]
	v_mov_b32_e32 v50, v119
	v_mul_f32_e32 v78, v78, v95
	v_lshlrev_b32_e32 v92, 2, v50
	v_ashrrev_i32_e32 v93, 31, v92
	v_lshl_add_u64 v[88:89], v[92:93], 2, s[10:11]
	global_load_dwordx4 v[188:191], v[88:89], off
	global_load_dwordx4 v[192:195], v[88:89], off offset:64
	global_load_dwordx4 v[196:199], v[88:89], off offset:128
	global_load_dwordx4 v[200:203], v[88:89], off offset:192
	global_load_dwordx4 v[204:207], v[88:89], off offset:256
	global_load_dwordx4 v[208:211], v[88:89], off offset:320
	global_load_dwordx4 v[212:215], v[88:89], off offset:384
	global_load_dwordx4 v[216:219], v[88:89], off offset:448
	s_waitcnt vmcnt(0)
; __device__ __forceinline__ void phase_attn(KP P, char* smem, const int wv) {
;     ...
;       for (int qt = 0; qt < 2; ++qt) {
;         float rl = 1.f / lrun[qt];
;         float ss = 0.f;
; #pragma unroll
;         for (int et = 0; et < 8; ++et) {
;           f32x4 o1 = *(const f32x4*)(sO + (rg * 32 + qt * 16 + fr) * A_LDO + et * 16 + fq * 4);
;           f32x4 o = oacc[qt][et] * rl - o1 * lam;
;           oacc[qt][et] = o;
;           ss += o[0] * o[0] + o[1] * o[1] + o[2] * o[2] + o[3] * o[3];
;         }
;         ss = xsum_16_32(ss);
;         float rstd = rsqrtf(ss * (1.f / 128.f) + EPS) * (1.f - LAMBDA_INIT);
;         bfu* dst = ao + (size_t)(qrow0 + rg * 32 + qt * 16 + fr) * 1024 + h * 128;
;         int fqe = fq;
;         asm volatile("" : "+v"(fqe));
; #pragma unroll
;         for (int et = 0; et < 8; ++et) {
;           int e0 = et * 16 + fqe * 4;
;           f32x4 sw = *(const f32x4*)(subln + e0);
;           uint2 pk;
;           pk.x = cvt_pk_bf16(oacc[qt][et][0] * rstd * sw[0], oacc[qt][et][1] * rstd * sw[1]);
;           pk.y = cvt_pk_bf16(oacc[qt][et][2] * rstd * sw[2], oacc[qt][et][3] * rstd * sw[3]);
;           *(uint2*)(dst + e0) = pk;
;         }
	v_mul_f32_e32 v50, v188, v78
	v_mul_f32_e32 v78, v79, v95
	v_mul_f32_e32 v51, v189, v78
	v_cvt_pk_bf16_f32 v78, v50, v51
	v_mul_f32_e32 v50, v80, v95
	v_mul_f32_e32 v51, v81, v95
	v_mul_f32_e32 v50, v190, v50
	v_mul_f32_e32 v51, v191, v51
	v_cvt_pk_bf16_f32 v79, v50, v51
	v_lshl_add_u64 v[50:51], v[92:93], 1, v[90:91]
	global_store_dwordx2 v[50:51], v[78:79], off
	v_mul_f32_e32 v52, v74, v95
	v_mul_f32_e32 v53, v75, v95
	v_mul_f32_e32 v74, v77, v95
	v_mul_f32_e32 v52, v192, v52
	v_mul_f32_e32 v53, v193, v53
	v_cvt_pk_bf16_f32 v52, v52, v53
	v_mul_f32_e32 v53, v76, v95
	v_mul_f32_e32 v53, v194, v53
	v_mul_f32_e32 v74, v195, v74
	v_cvt_pk_bf16_f32 v53, v53, v74
	global_store_dwordx2 v[50:51], v[52:53], off offset:32
	v_mul_f32_e32 v52, v70, v95
	v_mul_f32_e32 v53, v71, v95
	v_mul_f32_e32 v70, v73, v95
	v_mul_f32_e32 v52, v52, v196
	v_mul_f32_e32 v53, v53, v197
	v_cvt_pk_bf16_f32 v52, v52, v53
	v_mul_f32_e32 v53, v72, v95
	v_mul_f32_e32 v53, v53, v198
	v_mul_f32_e32 v70, v70, v199
	v_cvt_pk_bf16_f32 v53, v53, v70
	global_store_dwordx2 v[50:51], v[52:53], off offset:64
	v_mul_f32_e32 v52, v66, v95
	v_mul_f32_e32 v53, v67, v95
	v_mul_f32_e32 v66, v69, v95
	v_mul_f32_e32 v52, v52, v200
	v_mul_f32_e32 v53, v53, v201
	v_cvt_pk_bf16_f32 v52, v52, v53
	v_mul_f32_e32 v53, v68, v95
	v_mul_f32_e32 v53, v53, v202
	v_mul_f32_e32 v66, v66, v203
	v_cvt_pk_bf16_f32 v53, v53, v66
	global_store_dwordx2 v[50:51], v[52:53], off offset:96
	v_mul_f32_e32 v52, v62, v95
	v_mul_f32_e32 v53, v63, v95
	v_mul_f32_e32 v62, v65, v95
	v_mul_f32_e32 v52, v52, v204
	v_mul_f32_e32 v53, v53, v205
	v_cvt_pk_bf16_f32 v52, v52, v53
	v_mul_f32_e32 v53, v64, v95
	v_mul_f32_e32 v53, v53, v206
	v_mul_f32_e32 v62, v62, v207
	v_cvt_pk_bf16_f32 v53, v53, v62
	global_store_dwordx2 v[50:51], v[52:53], off offset:128
	v_mul_f32_e32 v52, v58, v95
	v_mul_f32_e32 v53, v59, v95
	v_mul_f32_e32 v58, v61, v95
	v_mul_f32_e32 v52, v52, v208
	v_mul_f32_e32 v53, v53, v209
	v_cvt_pk_bf16_f32 v52, v52, v53
	v_mul_f32_e32 v53, v60, v95
	v_mul_f32_e32 v53, v53, v210
	v_mul_f32_e32 v58, v58, v211
	v_cvt_pk_bf16_f32 v53, v53, v58
	global_store_dwordx2 v[50:51], v[52:53], off offset:160
	v_mul_f32_e32 v52, v54, v95
	v_mul_f32_e32 v53, v55, v95
	v_mul_f32_e32 v54, v57, v95
	v_mul_f32_e32 v52, v52, v212
	v_mul_f32_e32 v53, v53, v213
	v_cvt_pk_bf16_f32 v52, v52, v53
	v_mul_f32_e32 v53, v56, v95
	v_mul_f32_e32 v53, v53, v214
	v_mul_f32_e32 v54, v54, v215
	v_cvt_pk_bf16_f32 v53, v53, v54
	global_store_dwordx2 v[50:51], v[52:53], off offset:192
	v_mul_f32_e32 v56, v86, v95
	v_mul_f32_e32 v52, v56, v216
	v_mul_f32_e32 v56, v87, v95
	v_mul_f32_e32 v53, v56, v217
	v_cvt_pk_bf16_f32 v52, v52, v53
	v_mul_f32_e32 v53, v84, v95
	v_mul_f32_e32 v53, v53, v218
	v_mul_f32_e32 v54, v85, v95
	v_mul_f32_e32 v54, v54, v219
	v_cvt_pk_bf16_f32 v53, v53, v54
	global_store_dwordx2 v[50:51], v[52:53], off offset:224
	v_div_scale_f32 v50, s[8:9], v94, v94, 1.0
	v_rcp_f32_e32 v51, v50
	s_nop 0
	v_fma_f32 v52, -v50, v51, 1.0
	v_fmac_f32_e32 v51, v52, v51
	v_div_scale_f32 v52, vcc, 1.0, v94, 1.0
	v_mul_f32_e32 v53, v52, v51
	v_fma_f32 v54, -v50, v53, v52
	v_fmac_f32_e32 v53, v54, v51
	v_fma_f32 v50, -v50, v53, v52
	v_div_fmas_f32 v50, v50, v51, v53
	v_div_fixup_f32 v56, v50, v94, 1.0
	ds_read_b128 v[220:223], v182 offset:8448
	ds_read_b128 v[224:227], v182 offset:8512
	ds_read_b128 v[228:231], v182 offset:8576
	ds_read_b128 v[232:235], v182 offset:8640
	s_waitcnt lgkmcnt(0)
	v_pk_mul_f32 v[52:53], v[124:125], v[222:223]
	v_pk_mul_f32 v[50:51], v[122:123], v[220:221]
	v_pk_fma_f32 v[48:49], v[48:49], v[56:57], v[52:53] op_sel_hi:[1,0,1] neg_lo:[0,0,1] neg_hi:[0,0,1]
	v_pk_fma_f32 v[50:51], v[46:47], v[56:57], v[50:51] op_sel_hi:[1,0,1] neg_lo:[0,0,1] neg_hi:[0,0,1]
	s_waitcnt lgkmcnt(0)
	v_pk_mul_f32 v[52:53], v[122:123], v[224:225]
	v_mul_f32_e32 v57, v51, v51
	v_fmac_f32_e32 v57, v50, v50
	v_fmac_f32_e32 v57, v48, v48
	v_fmac_f32_e32 v57, v49, v49
	v_pk_mul_f32 v[46:47], v[124:125], v[226:227]
	v_pk_fma_f32 v[42:43], v[42:43], v[56:57], v[52:53] op_sel_hi:[1,0,1] neg_lo:[0,0,1] neg_hi:[0,0,1]
	v_pk_fma_f32 v[44:45], v[44:45], v[56:57], v[46:47] op_sel_hi:[1,0,1] neg_lo:[0,0,1] neg_hi:[0,0,1]
	v_mul_f32_e32 v46, v43, v43
	v_fmac_f32_e32 v46, v42, v42
	v_fmac_f32_e32 v46, v44, v44
	v_fmac_f32_e32 v46, v45, v45
	v_add_f32_e32 v57, v57, v46
	s_waitcnt lgkmcnt(0)
	v_pk_mul_f32 v[52:53], v[122:123], v[228:229]
	v_pk_mul_f32 v[46:47], v[124:125], v[230:231]
	v_pk_fma_f32 v[38:39], v[38:39], v[56:57], v[52:53] op_sel_hi:[1,0,1] neg_lo:[0,0,1] neg_hi:[0,0,1]
	v_pk_fma_f32 v[40:41], v[40:41], v[56:57], v[46:47] op_sel_hi:[1,0,1] neg_lo:[0,0,1] neg_hi:[0,0,1]
	v_mul_f32_e32 v46, v39, v39
	v_fmac_f32_e32 v46, v38, v38
	v_fmac_f32_e32 v46, v40, v40
	v_fmac_f32_e32 v46, v41, v41
	v_add_f32_e32 v57, v57, v46
	s_waitcnt lgkmcnt(0)
	v_pk_mul_f32 v[52:53], v[122:123], v[232:233]
	v_pk_mul_f32 v[46:47], v[124:125], v[234:235]
	v_pk_fma_f32 v[34:35], v[34:35], v[56:57], v[52:53] op_sel_hi:[1,0,1] neg_lo:[0,0,1] neg_hi:[0,0,1]
	ds_read_b128 v[220:223], v182 offset:8704
	ds_read_b128 v[224:227], v182 offset:8768
	ds_read_b128 v[228:231], v182 offset:8832
	ds_read_b128 v[232:235], v182 offset:8896
	v_pk_fma_f32 v[36:37], v[36:37], v[56:57], v[46:47] op_sel_hi:[1,0,1] neg_lo:[0,0,1] neg_hi:[0,0,1]
	v_mul_f32_e32 v46, v35, v35
	v_fmac_f32_e32 v46, v34, v34
	v_fmac_f32_e32 v46, v36, v36
	v_fmac_f32_e32 v46, v37, v37
	v_add_f32_e32 v57, v57, v46
	s_waitcnt lgkmcnt(0)
; __device__ __forceinline__ void phase_attn(KP P, char* smem, const int wv) {
;     ...
;       for (int qt = 0; qt < 2; ++qt) {
;         float rl = 1.f / lrun[qt];
;         float ss = 0.f;
; #pragma unroll
;         for (int et = 0; et < 8; ++et) {
;           f32x4 o1 = *(const f32x4*)(sO + (rg * 32 + qt * 16 + fr) * A_LDO + et * 16 + fq * 4);
;           f32x4 o = oacc[qt][et] * rl - o1 * lam;
;           oacc[qt][et] = o;
;           ss += o[0] * o[0] + o[1] * o[1] + o[2] * o[2] + o[3] * o[3];
;         }
;         ss = xsum_16_32(ss);
;         float rstd = rsqrtf(ss * (1.f / 128.f) + EPS) * (1.f - LAMBDA_INIT);
;         bfu* dst = ao + (size_t)(qrow0 + rg * 32 + qt * 16 + fr) * 1024 + h * 128;
;         int fqe = fq;
;         asm volatile("" : "+v"(fqe));
; #pragma unroll
;         for (int et = 0; et < 8; ++et) {
;           int e0 = et * 16 + fqe * 4;
;           f32x4 sw = *(const f32x4*)(subln + e0);
;           uint2 pk;
;           pk.x = cvt_pk_bf16(oacc[qt][et][0] * rstd * sw[0], oacc[qt][et][1] * rstd * sw[1]);
;           pk.y = cvt_pk_bf16(oacc[qt][et][2] * rstd * sw[2], oacc[qt][et][3] * rstd * sw[3]);
;           *(uint2*)(dst + e0) = pk;
;         }
	v_pk_mul_f32 v[52:53], v[122:123], v[220:221]
	v_pk_mul_f32 v[46:47], v[124:125], v[222:223]
	v_pk_fma_f32 v[30:31], v[30:31], v[56:57], v[52:53] op_sel_hi:[1,0,1] neg_lo:[0,0,1] neg_hi:[0,0,1]
	v_pk_fma_f32 v[32:33], v[32:33], v[56:57], v[46:47] op_sel_hi:[1,0,1] neg_lo:[0,0,1] neg_hi:[0,0,1]
	v_mul_f32_e32 v46, v31, v31
	v_fmac_f32_e32 v46, v30, v30
	v_fmac_f32_e32 v46, v32, v32
	v_fmac_f32_e32 v46, v33, v33
	v_add_f32_e32 v57, v57, v46
	s_waitcnt lgkmcnt(0)
	v_pk_mul_f32 v[52:53], v[122:123], v[224:225]
	v_pk_mul_f32 v[46:47], v[124:125], v[226:227]
	v_pk_fma_f32 v[26:27], v[26:27], v[56:57], v[52:53] op_sel_hi:[1,0,1] neg_lo:[0,0,1] neg_hi:[0,0,1]
	v_pk_fma_f32 v[28:29], v[28:29], v[56:57], v[46:47] op_sel_hi:[1,0,1] neg_lo:[0,0,1] neg_hi:[0,0,1]
	v_mul_f32_e32 v46, v27, v27
	v_fmac_f32_e32 v46, v26, v26
	v_fmac_f32_e32 v46, v28, v28
	v_fmac_f32_e32 v46, v29, v29
	v_add_f32_e32 v57, v57, v46
	s_waitcnt lgkmcnt(0)
	v_pk_mul_f32 v[52:53], v[122:123], v[228:229]
	v_pk_mul_f32 v[46:47], v[124:125], v[230:231]
	v_pk_fma_f32 v[22:23], v[22:23], v[56:57], v[52:53] op_sel_hi:[1,0,1] neg_lo:[0,0,1] neg_hi:[0,0,1]
	v_pk_fma_f32 v[24:25], v[24:25], v[56:57], v[46:47] op_sel_hi:[1,0,1] neg_lo:[0,0,1] neg_hi:[0,0,1]
	v_mul_f32_e32 v46, v23, v23
	v_fmac_f32_e32 v46, v22, v22
	v_fmac_f32_e32 v46, v24, v24
	v_fmac_f32_e32 v46, v25, v25
	v_add_f32_e32 v57, v57, v46
	s_waitcnt lgkmcnt(0)
	v_pk_mul_f32 v[52:53], v[122:123], v[232:233]
	v_pk_mul_f32 v[46:47], v[124:125], v[234:235]
	v_pk_fma_f32 v[18:19], v[18:19], v[56:57], v[52:53] op_sel_hi:[1,0,1] neg_lo:[0,0,1] neg_hi:[0,0,1]
	v_mov_b32_e32 v52, v119
	v_pk_fma_f32 v[20:21], v[20:21], v[56:57], v[46:47] op_sel_hi:[1,0,1] neg_lo:[0,0,1] neg_hi:[0,0,1]
	v_lshlrev_b32_e32 v54, 2, v52
	v_ashrrev_i32_e32 v55, 31, v54
	v_lshl_add_u64 v[52:53], v[54:55], 2, s[10:11]
	v_mul_f32_e32 v46, v19, v19
	v_fmac_f32_e32 v46, v18, v18
	v_fmac_f32_e32 v46, v20, v20
	v_fmac_f32_e32 v46, v21, v21
	v_add_f32_e32 v46, v57, v46
	v_mov_b32_e32 v47, v46
	s_nop 1
	v_permlane16_swap_b32_e32 v46, v47
	v_add_f32_e32 v46, v46, v47
	v_mov_b32_e32 v47, v46
	s_nop 1
	v_permlane32_swap_b32_e32 v46, v47
	v_add_f32_e32 v46, v46, v47
	v_fmamk_f32 v46, v46, 0x3c000000, v146
	v_cmp_gt_f32_e32 vcc, s33, v46
	v_mul_f32_e32 v47, 0x4b800000, v46
	s_nop 0
	v_cndmask_b32_e32 v46, v46, v47, vcc
	v_rsq_f32_e32 v46, v46
	s_nop 0
	v_mul_f32_e32 v47, 0x45800000, v46
	v_cndmask_b32_e32 v46, v46, v47, vcc
	v_mul_f32_e32 v56, 0x3f24fd5c, v46
	v_add_u32_e32 v46, 16, v82
	v_ashrrev_i32_e32 v47, 31, v46
	v_lshlrev_b64 v[46:47], 11, v[46:47]
	v_lshl_add_u64 v[46:47], s[6:7], 0, v[46:47]
	v_mul_f32_e32 v50, v50, v56
	v_mul_f32_e32 v51, v51, v56
	v_mul_f32_e32 v48, v48, v56
	v_mul_f32_e32 v49, v49, v56
	v_lshl_add_u64 v[46:47], v[54:55], 1, v[46:47]
	v_mul_f32_e32 v42, v42, v56
	v_mul_f32_e32 v43, v43, v56
	v_mul_f32_e32 v38, v38, v56
	v_mul_f32_e32 v39, v39, v56
	v_mul_f32_e32 v34, v34, v56
	v_mul_f32_e32 v35, v35, v56
	v_mul_f32_e32 v30, v30, v56
	v_mul_f32_e32 v31, v31, v56
	v_mul_f32_e32 v26, v26, v56
	v_mul_f32_e32 v27, v27, v56
	v_mul_f32_e32 v22, v22, v56
	v_mul_f32_e32 v23, v23, v56
	v_mul_f32_e32 v18, v18, v56
	v_mul_f32_e32 v19, v19, v56
	v_mul_f32_e32 v50, v188, v50
	v_mul_f32_e32 v51, v189, v51
	v_cvt_pk_bf16_f32 v50, v50, v51
	v_mul_f32_e32 v48, v190, v48
	v_mul_f32_e32 v49, v191, v49
	v_cvt_pk_bf16_f32 v51, v48, v49
	global_store_dwordx2 v[46:47], v[50:51], off
	v_mul_f32_e32 v42, v192, v42
	v_mul_f32_e32 v43, v193, v43
	v_cvt_pk_bf16_f32 v42, v42, v43
	v_mul_f32_e32 v43, v44, v56
	v_mul_f32_e32 v43, v194, v43
	v_mul_f32_e32 v44, v45, v56
	v_mul_f32_e32 v44, v195, v44
	v_cvt_pk_bf16_f32 v43, v43, v44
	global_store_dwordx2 v[46:47], v[42:43], off offset:32
	v_mul_f32_e32 v38, v38, v196
	v_mul_f32_e32 v39, v39, v197
	v_cvt_pk_bf16_f32 v38, v38, v39
	v_mul_f32_e32 v39, v40, v56
	v_mul_f32_e32 v39, v39, v198
	v_mul_f32_e32 v40, v41, v56
	v_mul_f32_e32 v40, v40, v199
	v_cvt_pk_bf16_f32 v39, v39, v40
	global_store_dwordx2 v[46:47], v[38:39], off offset:64
	v_mul_f32_e32 v34, v34, v200
	v_mul_f32_e32 v35, v35, v201
	v_cvt_pk_bf16_f32 v34, v34, v35
	v_mul_f32_e32 v35, v36, v56
	v_mul_f32_e32 v35, v35, v202
	v_mul_f32_e32 v36, v37, v56
	v_mul_f32_e32 v36, v36, v203
	v_cvt_pk_bf16_f32 v35, v35, v36
	global_store_dwordx2 v[46:47], v[34:35], off offset:96
	v_mul_f32_e32 v30, v30, v204
	v_mul_f32_e32 v31, v31, v205
	v_cvt_pk_bf16_f32 v30, v30, v31
	v_mul_f32_e32 v31, v32, v56
	v_mul_f32_e32 v31, v31, v206
	v_mul_f32_e32 v32, v33, v56
	v_mul_f32_e32 v32, v32, v207
	v_cvt_pk_bf16_f32 v31, v31, v32
	global_store_dwordx2 v[46:47], v[30:31], off offset:128
	v_mul_f32_e32 v26, v26, v208
	v_mul_f32_e32 v27, v27, v209
	v_cvt_pk_bf16_f32 v26, v26, v27
	v_mul_f32_e32 v27, v28, v56
	v_mul_f32_e32 v27, v27, v210
	v_mul_f32_e32 v28, v29, v56
	v_mul_f32_e32 v28, v28, v211
	v_cvt_pk_bf16_f32 v27, v27, v28
	global_store_dwordx2 v[46:47], v[26:27], off offset:160
	v_mul_f32_e32 v22, v22, v212
	v_mul_f32_e32 v23, v23, v213
	v_cvt_pk_bf16_f32 v22, v22, v23
	v_mul_f32_e32 v23, v24, v56
	v_mul_f32_e32 v23, v23, v214
	v_mul_f32_e32 v24, v25, v56
	v_mul_f32_e32 v24, v24, v215
	v_cvt_pk_bf16_f32 v23, v23, v24
	global_store_dwordx2 v[46:47], v[22:23], off offset:192
	v_mul_f32_e32 v18, v18, v216
	v_mul_f32_e32 v19, v19, v217
	v_cvt_pk_bf16_f32 v18, v18, v19
	v_mul_f32_e32 v19, v20, v56
	v_mul_f32_e32 v19, v19, v218
	v_mul_f32_e32 v20, v21, v56
	v_mul_f32_e32 v20, v20, v219
	v_cvt_pk_bf16_f32 v19, v19, v20
	global_store_dwordx2 v[46:47], v[18:19], off offset:224
	s_branch .LBB0_30
